# strategy 8 MFMA/VALU interleave: second-half exp2 + bf16 packs of each selected group issued in the shadow of the first five P.V MFMAs; ones vector hoisted out of the loop
# baseline (speedup 1.0000x reference)
; __device__ __forceinline__ void sel_group(const LAS bf16_t* Kt, const LAS bf16_t* Vt, LAS float* S, const bf16x8 qB0, const bf16x8 qB1, int jc, int rc, bool valid, bool masked, int tw64, int lr, int q) {
;     ...
;         const bf16x8 ones = (bf16x8){0x3F80, 0x3F80, 0x3F80, 0x3F80, 0x3F80, 0x3F80, 0x3F80, 0x3F80};
.Lsp_gdone_pre:
	v_mov_b32_e32 v178, 0x3f803f80
	v_mov_b32_e32 v179, 0x3f803f80
	v_mov_b32_e32 v180, 0x3f803f80
	v_mov_b32_e32 v181, 0x3f803f80
	s_branch .LBB0_1058

; __device__ __forceinline__ u32x4 pack8(const f32x4 a, const f32x4 b) { u32x4 w; w.x = cvt_pk_bf16(a[0], a[1]); w.y = cvt_pk_bf16(a[2], a[3]); w.z = cvt_pk_bf16(b[0], b[1]); w.w = cvt_pk_bf16(b[2], b[3]); return w; }
; #define LAS __attribute__((address_space(3)))
; __device__ __forceinline__ bf16x8 mk8(s16x4 a, s16x4 b) { return __builtin_shufflevector(a, b, 0, 1, 2, 3, 4, 5, 6, 7); }
; #define MFMA16(a, b, c) __builtin_amdgcn_mfma_f32_16x16x32_bf16((a), (b), (c), 0, 0, 0)
; __device__ __forceinline__ void sel_group(const LAS bf16_t* Kt, const LAS bf16_t* Vt, LAS float* S, const bf16x8 qB0, const bf16x8 qB1, int jc, int rc, bool valid, bool masked, int tw64, int lr, int q) {
;     ...
; #pragma unroll
;     for (int mt = 0; mt < 4; ++mt)
; #pragma unroll
;         for (int i = 0; i < 4; ++i) s[mt][i] = __builtin_amdgcn_exp2f(s[mt][i]);
;     bf16x8 pb[2];
;     pb[0] = __builtin_bit_cast(bf16x8, pg8::pack8(s[0], s[1]));
;     pb[1] = __builtin_bit_cast(bf16x8, pg8::pack8(s[2], s[3]));
;     if (anyneed) {
; #pragma unroll
;         for (int dt = 0; dt < 4; ++dt) acc[dt] = acc[dt] * alpha;
;         lc *= alpha;
;     }
;     f32x4 ls = (f32x4){0.f, 0.f, 0.f, 0.f};
;     {
;         const LAS bf16_t* vbase = Vt + (4 * q + (lr >> 2)) * 72 + 4 * (lr & 3);
;         const bf16x8 ones = (bf16x8){0x3F80, 0x3F80, 0x3F80, 0x3F80, 0x3F80, 0x3F80, 0x3F80, 0x3F80};
;         s16x4 vv[2][2];
;         vv[0][0] = vtr(vbase); vv[0][1] = vtr(vbase + 16 * 72);
; #pragma unroll
;         for (int it = 0; it < 8; ++it) {
;             const int kk = it >> 2, dt = it & 3;
;             if (it < 7) { const int kk2 = (it + 1) >> 2, dt2 = (it + 1) & 3; vv[(it + 1) & 1][0] = vtr(vbase + (32 * kk2) * 72 + 16 * dt2); vv[(it + 1) & 1][1] = vtr(vbase + (32 * kk2 + 16) * 72 + 16 * dt2); }
;             __builtin_amdgcn_sched_barrier(0);
;             const bf16x8 vf = mk8(vv[it & 1][0], vv[it & 1][1]);
;             __builtin_amdgcn_s_setprio(1); acc[dt] = MFMA16(vf, pb[kk], acc[dt]);
;             if (dt == 0) ls = MFMA16(ones, pb[kk], ls);
;             __builtin_amdgcn_s_setprio(0);
;             __builtin_amdgcn_sched_barrier(0);
;         }
;     }
;     if (valid) {
; #pragma unroll
;         for (int dt = 0; dt < 4; ++dt) *(LAS f32x4*)(Srow + 16 * dt + 4 * q) = acc[dt];
;         if (q == 0) Srow[64] = lc + ls[0];
.LBB0_1072:
	v_exp_f32_e32 v64, v64
	v_exp_f32_e32 v65, v65
	v_exp_f32_e32 v66, v66
	v_exp_f32_e32 v67, v67
	v_exp_f32_e32 v71, v71
	s_andn2_b64 vcc, exec, s[4:5]
	v_exp_f32_e32 v81, v68
	v_exp_f32_e32 v82, v69
	v_exp_f32_e32 v83, v70
	v_cvt_pk_bf16_f32 v68, v64, v65
	v_cvt_pk_bf16_f32 v69, v66, v67
	v_cvt_pk_bf16_f32 v70, v81, v82
	v_cvt_pk_bf16_f32 v71, v83, v71
	s_cbranch_vccnz .LBB0_1074
	v_pk_mul_f32 v[62:63], v[62:63], v[80:81] op_sel_hi:[1,0]
	v_pk_mul_f32 v[60:61], v[60:61], v[80:81] op_sel_hi:[1,0]
	v_pk_mul_f32 v[58:59], v[58:59], v[80:81] op_sel_hi:[1,0]
	v_pk_mul_f32 v[56:57], v[56:57], v[80:81] op_sel_hi:[1,0]
	v_pk_mul_f32 v[54:55], v[54:55], v[80:81] op_sel_hi:[1,0]
	v_pk_mul_f32 v[52:53], v[52:53], v[80:81] op_sel_hi:[1,0]
	v_pk_mul_f32 v[50:51], v[50:51], v[80:81] op_sel_hi:[1,0]
	v_pk_mul_f32 v[48:49], v[48:49], v[80:81] op_sel_hi:[1,0]
	v_mul_f32_e32 v84, v84, v80
.LBB0_1074:
	s_waitcnt lgkmcnt(0)
	v_mfma_f32_16x16x32_bf16 v[60:63], v[142:145], v[68:71], v[60:63]
	v_exp_f32_e32 v182, v72
	v_exp_f32_e32 v183, v73
	v_mfma_f32_16x16x32_bf16 v[80:83], v[178:181], v[68:71], 0
	v_exp_f32_e32 v184, v74
	v_exp_f32_e32 v185, v75
	v_mfma_f32_16x16x32_bf16 v[56:59], v[146:149], v[68:71], v[56:59]
	v_exp_f32_e32 v186, v76
	v_exp_f32_e32 v187, v77
	v_mfma_f32_16x16x32_bf16 v[120:123], v[150:153], v[68:71], v[52:55]
	v_exp_f32_e32 v188, v78
	v_exp_f32_e32 v189, v79
	v_mfma_f32_16x16x32_bf16 v[68:71], v[154:157], v[68:71], v[48:51]
	s_nop 0
	v_cvt_pk_bf16_f32 v64, v182, v183
	v_cvt_pk_bf16_f32 v65, v184, v185
	v_cvt_pk_bf16_f32 v66, v186, v187
	v_cvt_pk_bf16_f32 v67, v188, v189
	s_nop 1
	v_mfma_f32_16x16x32_bf16 v[52:55], v[158:161], v[64:67], v[60:63]
	v_mfma_f32_16x16x32_bf16 v[48:51], v[178:181], v[64:67], v[80:83]
	v_mfma_f32_16x16x32_bf16 v[56:59], v[162:165], v[64:67], v[56:59]
	v_mfma_f32_16x16x32_bf16 v[60:63], v[166:169], v[64:67], v[120:123]
	v_mfma_f32_16x16x32_bf16 v[64:67], v[170:173], v[64:67], v[68:71]
	s_nop 2
	s_and_saveexec_b64 s[4:5], s[76:77]
	s_cbranch_execz .LBB0_1077
	v_lshl_add_u32 v49, v89, 2, v119
	ds_write_b128 v49, v[52:55] offset:46080
	ds_write_b128 v49, v[56:59] offset:46144
	ds_write_b128 v49, v[60:63] offset:46208
	s_nop 0
	ds_write_b128 v49, v[64:67] offset:46272
	s_and_b64 exec, exec, s[68:69]
	v_add_f32_e32 v48, v84, v48
	ds_write_b32 v119, v48 offset:46336

; __device__ __forceinline__ u32x4 pack8(const f32x4 a, const f32x4 b) { u32x4 w; w.x = cvt_pk_bf16(a[0], a[1]); w.y = cvt_pk_bf16(a[2], a[3]); w.z = cvt_pk_bf16(b[0], b[1]); w.w = cvt_pk_bf16(b[2], b[3]); return w; }
; #define LAS __attribute__((address_space(3)))
; __device__ __forceinline__ bf16x8 mk8(s16x4 a, s16x4 b) { return __builtin_shufflevector(a, b, 0, 1, 2, 3, 4, 5, 6, 7); }
; #define MFMA16(a, b, c) __builtin_amdgcn_mfma_f32_16x16x32_bf16((a), (b), (c), 0, 0, 0)
; __device__ __forceinline__ void sel_group(const LAS bf16_t* Kt, const LAS bf16_t* Vt, LAS float* S, const bf16x8 qB0, const bf16x8 qB1, int jc, int rc, bool valid, bool masked, int tw64, int lr, int q) {
;     ...
; #pragma unroll
;     for (int mt = 0; mt < 4; ++mt)
; #pragma unroll
;         for (int i = 0; i < 4; ++i) s[mt][i] = __builtin_amdgcn_exp2f(s[mt][i]);
;     bf16x8 pb[2];
;     pb[0] = __builtin_bit_cast(bf16x8, pg8::pack8(s[0], s[1]));
;     pb[1] = __builtin_bit_cast(bf16x8, pg8::pack8(s[2], s[3]));
;     if (anyneed) {
; #pragma unroll
;         for (int dt = 0; dt < 4; ++dt) acc[dt] = acc[dt] * alpha;
;         lc *= alpha;
;     }
;     f32x4 ls = (f32x4){0.f, 0.f, 0.f, 0.f};
;     {
;         const LAS bf16_t* vbase = Vt + (4 * q + (lr >> 2)) * 72 + 4 * (lr & 3);
;         const bf16x8 ones = (bf16x8){0x3F80, 0x3F80, 0x3F80, 0x3F80, 0x3F80, 0x3F80, 0x3F80, 0x3F80};
;         s16x4 vv[2][2];
;         vv[0][0] = vtr(vbase); vv[0][1] = vtr(vbase + 16 * 72);
; #pragma unroll
;         for (int it = 0; it < 8; ++it) {
;             const int kk = it >> 2, dt = it & 3;
;             if (it < 7) { const int kk2 = (it + 1) >> 2, dt2 = (it + 1) & 3; vv[(it + 1) & 1][0] = vtr(vbase + (32 * kk2) * 72 + 16 * dt2); vv[(it + 1) & 1][1] = vtr(vbase + (32 * kk2 + 16) * 72 + 16 * dt2); }
;             __builtin_amdgcn_sched_barrier(0);
;             const bf16x8 vf = mk8(vv[it & 1][0], vv[it & 1][1]);
;             __builtin_amdgcn_s_setprio(1); acc[dt] = MFMA16(vf, pb[kk], acc[dt]);
;             if (dt == 0) ls = MFMA16(ones, pb[kk], ls);
;             __builtin_amdgcn_s_setprio(0);
;             __builtin_amdgcn_sched_barrier(0);
;         }
;     }
;     if (valid) {
; #pragma unroll
;         for (int dt = 0; dt < 4; ++dt) *(LAS f32x4*)(Srow + 16 * dt + 4 * q) = acc[dt];
;         if (q == 0) Srow[64] = lc + ls[0];
.LBB0_1086:
	v_exp_f32_e32 v44, v64
	v_exp_f32_e32 v45, v65
	v_exp_f32_e32 v46, v66
	v_exp_f32_e32 v47, v67
	v_exp_f32_e32 v64, v68
	s_andn2_b64 vcc, exec, s[4:5]
	v_exp_f32_e32 v65, v69
	v_exp_f32_e32 v66, v70
	v_exp_f32_e32 v67, v71
	v_cvt_pk_bf16_f32 v44, v44, v45
	v_cvt_pk_bf16_f32 v45, v46, v47
	v_cvt_pk_bf16_f32 v46, v64, v65
	v_cvt_pk_bf16_f32 v47, v66, v67
	s_cbranch_vccnz .LBB0_1088
	v_pk_mul_f32 v[62:63], v[62:63], v[78:79] op_sel_hi:[1,0]
	v_pk_mul_f32 v[60:61], v[60:61], v[78:79] op_sel_hi:[1,0]
	v_pk_mul_f32 v[58:59], v[58:59], v[78:79] op_sel_hi:[1,0]
	v_pk_mul_f32 v[56:57], v[56:57], v[78:79] op_sel_hi:[1,0]
	v_pk_mul_f32 v[54:55], v[54:55], v[78:79] op_sel_hi:[1,0]
	v_pk_mul_f32 v[52:53], v[52:53], v[78:79] op_sel_hi:[1,0]
	v_pk_mul_f32 v[50:51], v[50:51], v[78:79] op_sel_hi:[1,0]
	v_pk_mul_f32 v[48:49], v[48:49], v[78:79] op_sel_hi:[1,0]
	v_mul_f32_e32 v76, v76, v78
.LBB0_1088:
	s_waitcnt lgkmcnt(0)
	v_mfma_f32_16x16x32_bf16 v[60:63], v[142:145], v[44:47], v[60:63]
	v_exp_f32_e32 v182, v43
	v_exp_f32_e32 v183, v72
	v_exp_f32_e32 v184, v73
	v_exp_f32_e32 v185, v74
	v_exp_f32_e32 v186, v75
	v_mfma_f32_16x16x32_bf16 v[72:75], v[178:181], v[44:47], 0
	v_exp_f32_e32 v187, v40
	v_exp_f32_e32 v188, v41
	v_mfma_f32_16x16x32_bf16 v[56:59], v[146:149], v[44:47], v[56:59]
	v_exp_f32_e32 v189, v42
	v_mfma_f32_16x16x32_bf16 v[80:83], v[150:153], v[44:47], v[52:55]
	v_mfma_f32_16x16x32_bf16 v[68:71], v[154:157], v[44:47], v[48:51]
	s_nop 0
	v_cvt_pk_bf16_f32 v40, v183, v184
	v_cvt_pk_bf16_f32 v41, v185, v186
	v_cvt_pk_bf16_f32 v42, v187, v188
	v_cvt_pk_bf16_f32 v43, v189, v182
	s_nop 1
	v_mfma_f32_16x16x32_bf16 v[48:51], v[158:161], v[40:43], v[60:63]
	v_mfma_f32_16x16x32_bf16 v[44:47], v[178:181], v[40:43], v[72:75]
	v_mfma_f32_16x16x32_bf16 v[52:55], v[162:165], v[40:43], v[56:59]
	v_mfma_f32_16x16x32_bf16 v[56:59], v[166:169], v[40:43], v[80:83]
	v_mfma_f32_16x16x32_bf16 v[40:43], v[170:173], v[40:43], v[68:71]
	s_nop 2
	s_and_saveexec_b64 s[4:5], s[74:75]
	s_cbranch_execz .LBB0_1091
	v_lshl_add_u32 v45, v89, 2, v79
	ds_write_b128 v45, v[48:51] offset:46080
	ds_write_b128 v45, v[52:55] offset:46144
	ds_write_b128 v45, v[56:59] offset:46208
	s_nop 0
	ds_write_b128 v45, v[40:43] offset:46272
	s_and_b64 exec, exec, s[68:69]
	v_add_f32_e32 v40, v76, v44
	ds_write_b32 v79, v40 offset:46336

; __device__ __forceinline__ u32x4 pack8(const f32x4 a, const f32x4 b) { u32x4 w; w.x = cvt_pk_bf16(a[0], a[1]); w.y = cvt_pk_bf16(a[2], a[3]); w.z = cvt_pk_bf16(b[0], b[1]); w.w = cvt_pk_bf16(b[2], b[3]); return w; }
; #define LAS __attribute__((address_space(3)))
; __device__ __forceinline__ bf16x8 mk8(s16x4 a, s16x4 b) { return __builtin_shufflevector(a, b, 0, 1, 2, 3, 4, 5, 6, 7); }
; #define MFMA16(a, b, c) __builtin_amdgcn_mfma_f32_16x16x32_bf16((a), (b), (c), 0, 0, 0)
; __device__ __forceinline__ void sel_group(const LAS bf16_t* Kt, const LAS bf16_t* Vt, LAS float* S, const bf16x8 qB0, const bf16x8 qB1, int jc, int rc, bool valid, bool masked, int tw64, int lr, int q) {
;     ...
; #pragma unroll
;     for (int mt = 0; mt < 4; ++mt)
; #pragma unroll
;         for (int i = 0; i < 4; ++i) s[mt][i] = __builtin_amdgcn_exp2f(s[mt][i]);
;     bf16x8 pb[2];
;     pb[0] = __builtin_bit_cast(bf16x8, pg8::pack8(s[0], s[1]));
;     pb[1] = __builtin_bit_cast(bf16x8, pg8::pack8(s[2], s[3]));
;     if (anyneed) {
; #pragma unroll
;         for (int dt = 0; dt < 4; ++dt) acc[dt] = acc[dt] * alpha;
;         lc *= alpha;
;     }
;     f32x4 ls = (f32x4){0.f, 0.f, 0.f, 0.f};
;     {
;         const LAS bf16_t* vbase = Vt + (4 * q + (lr >> 2)) * 72 + 4 * (lr & 3);
;         const bf16x8 ones = (bf16x8){0x3F80, 0x3F80, 0x3F80, 0x3F80, 0x3F80, 0x3F80, 0x3F80, 0x3F80};
;         s16x4 vv[2][2];
;         vv[0][0] = vtr(vbase); vv[0][1] = vtr(vbase + 16 * 72);
; #pragma unroll
;         for (int it = 0; it < 8; ++it) {
;             const int kk = it >> 2, dt = it & 3;
;             if (it < 7) { const int kk2 = (it + 1) >> 2, dt2 = (it + 1) & 3; vv[(it + 1) & 1][0] = vtr(vbase + (32 * kk2) * 72 + 16 * dt2); vv[(it + 1) & 1][1] = vtr(vbase + (32 * kk2 + 16) * 72 + 16 * dt2); }
;             __builtin_amdgcn_sched_barrier(0);
;             const bf16x8 vf = mk8(vv[it & 1][0], vv[it & 1][1]);
;             __builtin_amdgcn_s_setprio(1); acc[dt] = MFMA16(vf, pb[kk], acc[dt]);
;             if (dt == 0) ls = MFMA16(ones, pb[kk], ls);
;             __builtin_amdgcn_s_setprio(0);
;             __builtin_amdgcn_sched_barrier(0);
;         }
;     }
;     if (valid) {
; #pragma unroll
;         for (int dt = 0; dt < 4; ++dt) *(LAS f32x4*)(Srow + 16 * dt + 4 * q) = acc[dt];
;         if (q == 0) Srow[64] = lc + ls[0];
;     }
.LBB0_1100:
	v_exp_f32_e32 v36, v56
	v_exp_f32_e32 v37, v57
	v_exp_f32_e32 v38, v58
	v_exp_f32_e32 v39, v59
	v_exp_f32_e32 v56, v60
	s_andn2_b64 vcc, exec, s[4:5]
	v_exp_f32_e32 v57, v61
	v_exp_f32_e32 v58, v62
	v_exp_f32_e32 v59, v63
	v_cvt_pk_bf16_f32 v36, v36, v37
	v_cvt_pk_bf16_f32 v37, v38, v39
	v_cvt_pk_bf16_f32 v38, v56, v57
	v_cvt_pk_bf16_f32 v39, v58, v59
	s_cbranch_vccnz .LBB0_1102
	v_pk_mul_f32 v[54:55], v[54:55], v[70:71] op_sel_hi:[1,0]
	v_pk_mul_f32 v[52:53], v[52:53], v[70:71] op_sel_hi:[1,0]
	v_pk_mul_f32 v[50:51], v[50:51], v[70:71] op_sel_hi:[1,0]
	v_pk_mul_f32 v[48:49], v[48:49], v[70:71] op_sel_hi:[1,0]
	v_pk_mul_f32 v[46:47], v[46:47], v[70:71] op_sel_hi:[1,0]
	v_pk_mul_f32 v[44:45], v[44:45], v[70:71] op_sel_hi:[1,0]
	v_pk_mul_f32 v[42:43], v[42:43], v[70:71] op_sel_hi:[1,0]
	v_pk_mul_f32 v[40:41], v[40:41], v[70:71] op_sel_hi:[1,0]
	v_mul_f32_e32 v68, v68, v70
.LBB0_1102:
	s_waitcnt lgkmcnt(0)
	v_mfma_f32_16x16x32_bf16 v[52:55], v[142:145], v[36:39], v[52:55]
	v_exp_f32_e32 v182, v35
	v_exp_f32_e32 v183, v64
	v_exp_f32_e32 v184, v65
	v_exp_f32_e32 v185, v66
	v_exp_f32_e32 v186, v67
	v_mfma_f32_16x16x32_bf16 v[64:67], v[178:181], v[36:39], 0
	v_exp_f32_e32 v187, v32
	v_exp_f32_e32 v188, v33
	v_mfma_f32_16x16x32_bf16 v[48:51], v[146:149], v[36:39], v[48:51]
	v_exp_f32_e32 v189, v34
	v_mfma_f32_16x16x32_bf16 v[72:75], v[150:153], v[36:39], v[44:47]
	v_mfma_f32_16x16x32_bf16 v[60:63], v[154:157], v[36:39], v[40:43]
	s_nop 0
	v_cvt_pk_bf16_f32 v32, v183, v184
	v_cvt_pk_bf16_f32 v33, v185, v186
	v_cvt_pk_bf16_f32 v34, v187, v188
	v_cvt_pk_bf16_f32 v35, v189, v182
	s_nop 1
	v_mfma_f32_16x16x32_bf16 v[40:43], v[158:161], v[32:35], v[52:55]
	v_mfma_f32_16x16x32_bf16 v[36:39], v[178:181], v[32:35], v[64:67]
	v_mfma_f32_16x16x32_bf16 v[44:47], v[162:165], v[32:35], v[48:51]
	v_mfma_f32_16x16x32_bf16 v[48:51], v[166:169], v[32:35], v[72:75]
	v_mfma_f32_16x16x32_bf16 v[32:35], v[170:173], v[32:35], v[60:63]
	s_nop 2
	s_and_saveexec_b64 s[4:5], s[70:71]
	s_cbranch_execz .LBB0_1056
	v_lshl_add_u32 v37, v89, 2, v71
	ds_write_b128 v37, v[40:43] offset:46080
	ds_write_b128 v37, v[44:47] offset:46144
	ds_write_b128 v37, v[48:51] offset:46208
	s_nop 0
	ds_write_b128 v37, v[32:35] offset:46272
	s_and_b64 exec, exec, s[68:69]
	s_cbranch_execz .LBB0_1056
	v_add_f32_e32 v32, v68, v36
	ds_write_b32 v71, v32 offset:46336
	s_branch .LBB0_1056
